# token_prep: gains and rope rows issued with the head loads; nsa_compress tail: second-layer weights and k-norm gains loaded in one batch
# speedup vs baseline: 1.0145x; 1.0018x over previous
.LBB0_324:
	s_andn2_saveexec_b64 s[44:45], s[44:45]
	v_mul_f32_e32 v1, v0, v0
	v_fmamk_f32 v2, v1, 0xbbbac73d, v224
	v_fmaak_f32 v2, v1, v2, 0xbd5c1c4e
	v_fmaak_f32 v2, v1, v2, 0x3e088382
	v_fmaak_f32 v2, v1, v2, 0xbeaaaa99
	v_mul_f32_e64 v2, |v0|, v2
	v_fma_f32 v1, v1, v2, |v0|
	s_or_b64 exec, exec, s[44:45]
	s_lshl_b32 s2, s26, 6
	s_and_b32 s84, s2, 0xfffff000
	s_and_b32 s2, s2, 0x3c0
	v_add_u32_e32 v18, s2, v83
	s_brev_b32 s2, -2
	v_bfi_b32 v0, s2, v1, v0
	v_mul_f32_e32 v2, 0.5, v3
	s_lshr_b32 s26, s26, 5
	v_add_f32_e32 v0, 1.0, v0
	s_lshl_b64 s[2:3], s[84:85], 1
	v_mul_f32_e32 v0, v2, v0
	s_add_u32 s2, s40, s2
	v_cvt_pk_bf16_f32 v0, v0, s0
	s_addc_u32 s3, s41, s3
	v_lshlrev_b32_e32 v128, 4, v8
	ds_write_b16 v10, v0 offset:528
	v_mul_u32_u24_e32 v0, 0x90, v82
	v_lshl_add_u64 v[28:29], s[2:3], 0, v[128:129]
	s_mov_b64 s[2:3], 0x11d40000
	v_add3_u32 v16, v9, v0, v128
	v_lshl_add_u64 v[20:21], v[28:29], 0, s[2:3]
	v_lshlrev_b32_e32 v128, 7, v82
	v_lshl_add_u64 v[30:31], v[20:21], 0, v[128:129]
	v_or_b32_e32 v32, 0x1000, v128
	v_mov_b32_e32 v33, v129
	v_or_b32_e32 v128, 0x1800, v128
	v_lshl_add_u64 v[12:13], v[20:21], 0, v[32:33]
	v_lshl_add_u64 v[20:21], v[20:21], 0, v[128:129]
	v_lshlrev_b32_e32 v17, 2, v8
	s_waitcnt lgkmcnt(0)
	s_barrier
	global_load_dwordx4 v[4:7], v[30:31], off
	global_load_dwordx4 v[8:11], v[30:31], off offset:2048
	ds_read_b128 v[0:3], v16
	ds_read_b128 v[24:27], v16 offset:64
	global_load_dwordx4 v[12:15], v[12:13], off
	s_mov_b64 s[2:3], 0x11d40040
	global_load_dwordx4 v[20:23], v[20:21], off
	v_lshl_add_u64 v[28:29], v[28:29], 0, s[2:3]
	s_load_dwordx2 s[2:3], s[36:37], 0x48
	s_lshl_b64 vcc, s[38:39], 2
	v_lshlrev_b32_e32 v195, 2, v82
	v_lshl_add_u64 v[216:217], v[28:29], 0, v[32:33]
	s_waitcnt lgkmcnt(0)
	s_add_u32 s2, s2, vcc_lo
	s_addc_u32 s3, s3, vcc_hi
	global_load_dword v196, v195, s[2:3]
	global_load_dword v197, v195, s[2:3] offset:64
	global_load_dword v198, v195, s[2:3] offset:128
	global_load_dword v199, v195, s[2:3] offset:192
	global_load_dwordx4 v[200:203], v[30:31], off offset:64
	global_load_dwordx4 v[204:207], v[30:31], off offset:2112
	global_load_dwordx4 v[208:211], v[216:217], off
	v_lshl_add_u64 v[216:217], v[28:29], 0, v[128:129]
	global_load_dwordx4 v[212:215], v[216:217], off
	s_lshl_b32 s2, s90, 12
	s_and_b32 s27, s2, 0x10000
	s_mov_b64 s[44:45], -1
	s_and_b64 vcc, exec, s[42:43]
	s_waitcnt vmcnt(11) lgkmcnt(1)
	v_mfma_f32_16x16x32_bf16 v[4:7], v[0:3], v[4:7], 0
	s_waitcnt vmcnt(10)
	v_mfma_f32_16x16x32_bf16 v[8:11], v[0:3], v[8:11], 0
	s_waitcnt vmcnt(9)
	v_mfma_f32_16x16x32_bf16 v[12:15], v[0:3], v[12:15], 0
	s_waitcnt vmcnt(8)
	v_mfma_f32_16x16x32_bf16 v[20:23], v[0:3], v[20:23], 0
	s_waitcnt vmcnt(3) lgkmcnt(0)
	v_mfma_f32_16x16x32_bf16 v[0:3], v[24:27], v[200:203], v[4:7]
	s_nop 2
	s_waitcnt vmcnt(2)
	v_mfma_f32_16x16x32_bf16 v[4:7], v[24:27], v[204:207], v[8:11]
	s_nop 2
	v_lshl_add_u64 v[8:9], v[28:29], 0, v[32:33]
	s_waitcnt vmcnt(1)
	v_mfma_f32_16x16x32_bf16 v[8:11], v[24:27], v[208:211], v[12:15]
	s_nop 2
	v_lshl_add_u64 v[12:13], v[28:29], 0, v[128:129]
	s_barrier
	s_waitcnt vmcnt(0)
	v_mfma_f32_16x16x32_bf16 v[12:15], v[24:27], v[212:215], v[20:23]
	v_or_b32_e32 v24, v18, v17
	s_nop 1
	v_or_b32_e32 v22, 1, v24
	v_or_b32_e32 v20, 2, v24
	v_or_b32_e32 v16, 3, v24
	s_cbranch_vccz .LBB0_328
	s_and_b32 s2, s26, 1
	s_lshl_b32 s3, s27, 1
	s_lshl_b32 s2, s2, 18
	s_or_b32 s2, s2, s3
	v_bitop3_b32 v17, v18, 28, v17 bitop3:0xc8
	s_add_u32 s2, s40, s2
	v_and_b32_e32 v26, 0xffffffe0, v18
	v_lshlrev_b32_e32 v18, 1, v17
	s_addc_u32 s3, s41, 0
	v_ashrrev_i32_e32 v27, 31, v26
	v_subrev_u32_e32 v19, 28, v18
	v_and_b32_e32 v18, 24, v18
	v_cmp_gt_u32_e64 s[42:43], 16, v17
	v_lshl_add_u64 v[26:27], v[26:27], 1, s[2:3]
	s_movk_i32 s28, 0x3ff
	v_cndmask_b32_e64 v128, v19, v18, s[42:43]
	v_lshlrev_b32_e32 v18, 11, v82
	v_mov_b32_e32 v19, v129
	v_lshl_add_u64 v[18:19], v[26:27], 0, v[18:19]
	s_mov_b64 s[2:3], 0x1f080000
	v_cvt_pk_bf16_f32 v21, v0, s0
	v_cmp_gt_i32_e32 vcc, s28, v24
	v_lshl_add_u64 v[26:27], v[18:19], 0, s[2:3]
	v_lshlrev_b64 v[28:29], 1, v[128:129]
	v_cndmask_b32_e32 v21, 0, v21, vcc
	v_lshl_add_u64 v[30:31], v[26:27], 0, v[28:29]
	s_mov_b64 s[2:3], 0x1f088000
	global_store_short v[30:31], v21, off
	v_cvt_pk_bf16_f32 v17, v4, s0
	v_lshl_add_u64 v[30:31], v[18:19], 0, s[2:3]
	v_cndmask_b32_e32 v17, 0, v17, vcc
	v_lshl_add_u64 v[32:33], v[30:31], 0, v[28:29]
	s_mov_b64 s[2:3], 0x1f090000
	global_store_short v[32:33], v17, off
	v_cvt_pk_bf16_f32 v17, v8, s0
	v_lshl_add_u64 v[32:33], v[18:19], 0, s[2:3]
	v_cndmask_b32_e32 v17, 0, v17, vcc
	v_lshl_add_u64 v[34:35], v[32:33], 0, v[28:29]
	s_mov_b64 s[2:3], 0x1f098000
	global_store_short v[34:35], v17, off
	v_cvt_pk_bf16_f32 v17, v12, s0
	v_lshl_add_u64 v[18:19], v[18:19], 0, s[2:3]
	v_cndmask_b32_e32 v17, 0, v17, vcc
	v_lshl_add_u64 v[28:29], v[18:19], 0, v[28:29]
	global_store_short v[28:29], v17, off
	v_bitop3_b32 v17, v24, 29, 1 bitop3:0xc8
	v_lshlrev_b32_e32 v21, 1, v17
	v_and_b32_e32 v23, 56, v21
	v_subrev_u32_e32 v23, 28, v23
	v_and_b32_e32 v21, 24, v21
	v_cmp_gt_u32_e64 s[42:43], 16, v17
	v_cvt_pk_bf16_f32 v25, v1, s0
	v_cmp_gt_i32_e32 vcc, s28, v22
	v_cndmask_b32_e64 v28, v23, v21, s[42:43]
	v_mov_b32_e32 v29, v129
	v_cndmask_b32_e32 v25, 0, v25, vcc
	v_or_b32_e32 v128, 1, v28
	v_lshl_add_u64 v[28:29], v[28:29], 1, v[26:27]
	global_store_short v[28:29], v25, off offset:2
	v_cvt_pk_bf16_f32 v17, v5, s0
	v_lshlrev_b64 v[28:29], 1, v[128:129]
	v_cndmask_b32_e32 v17, 0, v17, vcc
	v_lshl_add_u64 v[34:35], v[30:31], 0, v[28:29]
	global_store_short v[34:35], v17, off
	v_cvt_pk_bf16_f32 v17, v9, s0
	v_cndmask_b32_e32 v17, 0, v17, vcc
	v_lshl_add_u64 v[34:35], v[32:33], 0, v[28:29]
	global_store_short v[34:35], v17, off
	v_cvt_pk_bf16_f32 v17, v13, s0
	v_cndmask_b32_e32 v17, 0, v17, vcc
	v_lshl_add_u64 v[28:29], v[18:19], 0, v[28:29]
	global_store_short v[28:29], v17, off
	v_bitop3_b32 v17, v24, 30, 2 bitop3:0xc8
	v_lshlrev_b32_e32 v21, 1, v17
	v_and_b32_e32 v23, 56, v21
	v_subrev_u32_e32 v23, 28, v23
	v_and_b32_e32 v21, 24, v21
	v_cmp_gt_u32_e64 s[42:43], 16, v17
	v_cvt_pk_bf16_f32 v25, v2, s0
	v_cmp_gt_i32_e32 vcc, s28, v20
	v_cndmask_b32_e64 v28, v23, v21, s[42:43]
	v_mov_b32_e32 v29, v129
	v_cndmask_b32_e32 v25, 0, v25, vcc
	v_or_b32_e32 v128, 2, v28
	v_lshl_add_u64 v[28:29], v[28:29], 1, v[26:27]
	global_store_short v[28:29], v25, off offset:4
	v_cvt_pk_bf16_f32 v17, v6, s0
	v_lshlrev_b64 v[28:29], 1, v[128:129]
	v_cndmask_b32_e32 v17, 0, v17, vcc
	v_lshl_add_u64 v[34:35], v[30:31], 0, v[28:29]
	global_store_short v[34:35], v17, off
	v_cvt_pk_bf16_f32 v17, v10, s0
	v_cndmask_b32_e32 v17, 0, v17, vcc
	v_lshl_add_u64 v[34:35], v[32:33], 0, v[28:29]
	global_store_short v[34:35], v17, off
	v_cvt_pk_bf16_f32 v17, v14, s0
	v_cndmask_b32_e32 v17, 0, v17, vcc
	v_lshl_add_u64 v[28:29], v[18:19], 0, v[28:29]
	global_store_short v[28:29], v17, off
	v_bitop3_b32 v17, v24, 31, 3 bitop3:0xc8
	v_lshlrev_b32_e32 v21, 1, v17
	v_and_b32_e32 v23, 56, v21
	v_subrev_u32_e32 v23, 28, v23
	v_and_b32_e32 v21, 24, v21
	v_cmp_gt_u32_e64 s[42:43], 16, v17
	v_cvt_pk_bf16_f32 v25, v3, s0
	v_cmp_gt_i32_e32 vcc, s28, v16
	v_cndmask_b32_e64 v28, v23, v21, s[42:43]
	v_mov_b32_e32 v29, v129
	v_cndmask_b32_e32 v25, 0, v25, vcc
	v_or_b32_e32 v128, 3, v28
	v_lshl_add_u64 v[26:27], v[28:29], 1, v[26:27]
	global_store_short v[26:27], v25, off offset:6
	v_cvt_pk_bf16_f32 v17, v7, s0
	v_lshlrev_b64 v[26:27], 1, v[128:129]
	v_cndmask_b32_e32 v17, 0, v17, vcc
	v_lshl_add_u64 v[28:29], v[30:31], 0, v[26:27]
	global_store_short v[28:29], v17, off
	v_cvt_pk_bf16_f32 v17, v11, s0
	v_cndmask_b32_e32 v17, 0, v17, vcc
	v_lshl_add_u64 v[28:29], v[32:33], 0, v[26:27]
	global_store_short v[28:29], v17, off
	v_cvt_pk_bf16_f32 v17, v15, s0
	v_cndmask_b32_e32 v17, 0, v17, vcc
	v_lshl_add_u64 v[18:19], v[18:19], 0, v[26:27]
	global_store_short v[18:19], v17, off
	s_mov_b64 s[44:45], 0

.LBB0_331:
	s_or_saveexec_b64 s[42:43], s[42:43]
	v_mov_b32_e32 v23, 0
	v_lshlrev_b32_e32 v26, 2, v82
	s_xor_b64 exec, exec, s[42:43]
	s_cbranch_execz .LBB0_333
	v_add_f32_e32 v17, v17, v21
	v_fmamk_f32 v17, v17, 0x3c800000, v220
	s_mov_b32 s2, 0x800000
	v_cmp_gt_f32_e32 vcc, s2, v17
	v_mul_f32_e32 v21, 0x4b800000, v17
	v_mov_b32_e32 v32, v8
	v_cndmask_b32_e32 v17, v17, v21, vcc
	v_rsq_f32_e32 v17, v17
	v_mov_b32_e32 v33, v12
	v_mul_f32_e32 v21, 0x45800000, v17
	v_cndmask_b32_e32 v28, v17, v21, vcc
	v_mul_f32_e32 v0, v0, v28
	v_mul_f32_e32 v4, v4, v28
	v_pk_mul_f32 v[28:29], v[32:33], v[28:29] op_sel_hi:[1,0]
	v_mul_f32_e32 v0, v0, v196
	v_cvt_pk_bf16_f32 v0, v0, s0
	v_mul_f32_e32 v4, v4, v197
	v_cvt_pk_bf16_f32 v4, v4, s0
	global_store_short v[24:25], v0, off
	global_store_short v[24:25], v4, off offset:32
	v_pk_mul_f32 v[28:29], v[28:29], v[198:199]
	s_nop 0
	v_cvt_pk_bf16_f32 v23, v28, v29

.LBB0_335:
	s_or_saveexec_b64 s[42:43], s[42:43]
	v_mov_b32_e32 v8, 0
	s_xor_b64 exec, exec, s[42:43]
	s_cbranch_execz .LBB0_337
	v_add_f32_e32 v0, v0, v4
	v_fmamk_f32 v0, v0, 0x3c800000, v220
	s_mov_b32 s2, 0x800000
	v_cmp_gt_f32_e32 vcc, s2, v0
	v_mul_f32_e32 v4, 0x4b800000, v0
	v_mov_b32_e32 v12, v9
	v_cndmask_b32_e32 v0, v0, v4, vcc
	v_rsq_f32_e32 v0, v0
	s_nop 0
	v_mul_f32_e32 v4, 0x45800000, v0
	v_cndmask_b32_e32 v0, v0, v4, vcc
	v_mul_f32_e32 v1, v1, v0
	v_mul_f32_e32 v1, v1, v196
	v_mul_f32_e32 v4, v5, v0
	v_cvt_pk_bf16_f32 v1, v1, s0
	v_mul_f32_e32 v4, v4, v197
	v_cvt_pk_bf16_f32 v4, v4, s0
	global_store_short v[22:23], v1, off
	global_store_short v[22:23], v4, off offset:32
	s_nop 0
	v_pk_mul_f32 v[0:1], v[12:13], v[0:1] op_sel_hi:[1,0]
	v_pk_mul_f32 v[0:1], v[0:1], v[198:199]
	s_nop 0
	v_cvt_pk_bf16_f32 v8, v0, v1

.LBB0_339:
	s_or_saveexec_b64 s[42:43], s[42:43]
	v_mov_b32_e32 v8, 0
	s_xor_b64 exec, exec, s[42:43]
	s_cbranch_execz .LBB0_341
	v_add_f32_e32 v4, v4, v5
	v_fmamk_f32 v4, v4, 0x3c800000, v220
	s_mov_b32 s2, 0x800000
	v_cmp_gt_f32_e32 vcc, s2, v4
	v_mul_f32_e32 v5, 0x4b800000, v4
	v_mov_b32_e32 v12, v10
	v_cndmask_b32_e32 v4, v4, v5, vcc
	v_rsq_f32_e32 v4, v4
	v_mov_b32_e32 v13, v14
	v_mul_f32_e32 v5, 0x45800000, v4
	v_cndmask_b32_e32 v4, v4, v5, vcc
	v_mul_f32_e32 v2, v2, v4
	v_mul_f32_e32 v2, v2, v196
	v_mul_f32_e32 v5, v6, v4
	v_cvt_pk_bf16_f32 v2, v2, s0
	v_mul_f32_e32 v5, v5, v197
	v_cvt_pk_bf16_f32 v5, v5, s0
	global_store_short v[0:1], v2, off
	global_store_short v[0:1], v5, off offset:32
	v_pk_mul_f32 v[4:5], v[12:13], v[4:5] op_sel_hi:[1,0]
	v_pk_mul_f32 v[4:5], v[4:5], v[198:199]
	s_nop 0
	v_cvt_pk_bf16_f32 v8, v4, v5

.LBB0_343:
	s_or_saveexec_b64 s[42:43], s[42:43]
	v_mov_b32_e32 v0, 0
	s_xor_b64 exec, exec, s[42:43]
	s_cbranch_execz .LBB0_345
	v_add_f32_e32 v2, v20, v21
	v_fmamk_f32 v2, v2, 0x3c800000, v220
	s_mov_b32 s2, 0x800000
	v_mul_f32_e32 v6, 0x4b800000, v2
	v_cmp_gt_f32_e32 vcc, s2, v2
	v_mov_b32_e32 v14, v11
	s_nop 0
	v_cndmask_b32_e32 v2, v2, v6, vcc
	v_rsq_f32_e32 v2, v2
	s_nop 0
	v_mul_f32_e32 v6, 0x45800000, v2
	v_cndmask_b32_e32 v2, v2, v6, vcc
	v_mul_f32_e32 v6, v3, v2
	v_mul_f32_e32 v7, v7, v2
	v_pk_mul_f32 v[2:3], v[14:15], v[2:3] op_sel_hi:[1,0]
	s_waitcnt vmcnt(3)
	v_mul_f32_e32 v4, v6, v196
	s_waitcnt vmcnt(2)
	v_mul_f32_e32 v5, v7, v197
	v_pk_mul_f32 v[0:1], v[2:3], v[198:199]
	v_cvt_pk_bf16_f32 v2, v4, s0
	v_cvt_pk_bf16_f32 v0, v0, v1
	v_cvt_pk_bf16_f32 v3, v5, s0
	global_store_short v[16:17], v2, off
	global_store_short v[16:17], v3, off offset:32

.LBB0_359:
	s_or_b64 exec, exec, s[50:51]
	v_ashrrev_i32_e32 v7, 31, v6
	v_lshl_add_u64 v[60:61], v[6:7], 0, s[84:85]
	v_mov_b64_e32 v[6:7], s[42:43]
	v_mad_u64_u32 v[6:7], s[2:3], v60, s10, v[6:7]
	v_mad_i32_i24 v7, v61, s10, v7
	v_lshl_add_u64 v[6:7], v[128:129], 1, v[6:7]
	global_load_dwordx4 v[62:65], v[6:7], off
	global_load_dwordx4 v[66:69], v[6:7], off offset:16
	global_load_dwordx4 v[8:11], v[6:7], off offset:32
	global_load_dwordx4 v[12:15], v[6:7], off offset:48
	global_load_dwordx4 v[16:19], v[6:7], off offset:64
	global_load_dwordx4 v[20:23], v[6:7], off offset:80
	global_load_dwordx4 v[70:73], v[6:7], off offset:96
	global_load_dwordx4 v[74:77], v[6:7], off offset:112
	global_load_dwordx4 v[82:85], v[4:5], off offset:48
	global_load_dwordx4 v[86:89], v[4:5], off offset:32
	global_load_dwordx4 v[204:207], v[4:5], off offset:16
	global_load_dwordx4 v[208:211], v[4:5], off
	global_load_dwordx4 v[156:159], v[4:5], off offset:64
	global_load_dwordx4 v[160:163], v[4:5], off offset:80
	global_load_dwordx4 v[164:167], v[4:5], off offset:96
	global_load_dwordx4 v[168:171], v[4:5], off offset:112
	global_load_dwordx4 v[172:175], v[4:5], off offset:128
	global_load_dwordx4 v[176:179], v[4:5], off offset:144
	global_load_dwordx4 v[180:183], v[4:5], off offset:160
	global_load_dwordx4 v[184:187], v[4:5], off offset:176
	global_load_dwordx4 v[188:191], v[4:5], off offset:192
	global_load_dwordx4 v[192:195], v[4:5], off offset:208
	global_load_dwordx4 v[196:199], v[4:5], off offset:224
	global_load_dwordx4 v[200:203], v[4:5], off offset:240
	v_lshlrev_b64 v[216:217], 6, v[60:61]
	v_lshl_add_u64 v[216:217], s[46:47], 0, v[216:217]
	global_load_dwordx4 v[212:215], v[216:217], off offset:48
	global_load_dwordx4 v[240:243], v[216:217], off offset:32
	global_load_dwordx4 v[244:247], v[216:217], off offset:16
	global_load_dwordx4 v[248:251], v[216:217], off
	s_mov_b32 s2, 0x800000
	s_waitcnt vmcnt(27)
	v_and_b32_e32 v141, 0xffff0000, v62
	v_lshlrev_b32_e32 v140, 16, v62
	s_waitcnt vmcnt(25)
	v_and_b32_e32 v55, 0xffff0000, v8
	v_lshlrev_b32_e32 v54, 16, v8
	v_and_b32_e32 v53, 0xffff0000, v9
	v_lshlrev_b32_e32 v52, 16, v9
	v_and_b32_e32 v51, 0xffff0000, v10
	v_lshlrev_b32_e32 v50, 16, v10
	v_and_b32_e32 v49, 0xffff0000, v11
	v_lshlrev_b32_e32 v48, 16, v11
	s_waitcnt vmcnt(24)
	v_and_b32_e32 v47, 0xffff0000, v12
	v_lshlrev_b32_e32 v46, 16, v12
	v_and_b32_e32 v45, 0xffff0000, v13
	v_lshlrev_b32_e32 v44, 16, v13
	v_and_b32_e32 v43, 0xffff0000, v14
	v_lshlrev_b32_e32 v42, 16, v14
	v_and_b32_e32 v41, 0xffff0000, v15
	v_lshlrev_b32_e32 v40, 16, v15
	s_waitcnt vmcnt(23)
	v_and_b32_e32 v39, 0xffff0000, v16
	v_lshlrev_b32_e32 v38, 16, v16
	v_and_b32_e32 v37, 0xffff0000, v17
	v_lshlrev_b32_e32 v36, 16, v17
	v_and_b32_e32 v35, 0xffff0000, v18
	v_lshlrev_b32_e32 v34, 16, v18
	v_and_b32_e32 v33, 0xffff0000, v19
	v_lshlrev_b32_e32 v32, 16, v19
	s_waitcnt vmcnt(22)
	v_and_b32_e32 v31, 0xffff0000, v20
	v_lshlrev_b32_e32 v30, 16, v20
	v_and_b32_e32 v29, 0xffff0000, v21
	v_lshlrev_b32_e32 v28, 16, v21
	v_and_b32_e32 v27, 0xffff0000, v22
	v_lshlrev_b32_e32 v26, 16, v22
	v_and_b32_e32 v25, 0xffff0000, v23
	v_lshlrev_b32_e32 v24, 16, v23
	s_waitcnt vmcnt(21)
	v_and_b32_e32 v23, 0xffff0000, v70
	v_lshlrev_b32_e32 v22, 16, v70
	v_and_b32_e32 v21, 0xffff0000, v71
	v_lshlrev_b32_e32 v20, 16, v71
	v_and_b32_e32 v19, 0xffff0000, v72
	v_lshlrev_b32_e32 v18, 16, v72
	v_and_b32_e32 v17, 0xffff0000, v73
	v_lshlrev_b32_e32 v16, 16, v73
	s_waitcnt vmcnt(20)
	v_and_b32_e32 v9, 0xffff0000, v74
	v_lshlrev_b32_e32 v8, 16, v74
	v_and_b32_e32 v11, 0xffff0000, v75
	v_lshlrev_b32_e32 v10, 16, v75
	v_and_b32_e32 v13, 0xffff0000, v76
	v_lshlrev_b32_e32 v12, 16, v76
	v_and_b32_e32 v15, 0xffff0000, v77
	v_lshlrev_b32_e32 v14, 16, v77
	v_pk_mul_f32 v[142:143], v[140:141], v[140:141]
	v_and_b32_e32 v149, 0xffff0000, v63
	v_lshlrev_b32_e32 v148, 16, v63
	v_pk_mul_f32 v[62:63], v[148:149], v[148:149]
	v_add_f32_e32 v59, v142, v143
	v_lshlrev_b32_e32 v1, 16, v65
	v_and_b32_e32 v137, 0xffff0000, v65
	v_and_b32_e32 v65, 0xffff0000, v64
	v_lshlrev_b32_e32 v64, 16, v64
	v_add_f32_e32 v59, v59, v62
	v_pk_mul_f32 v[152:153], v[64:65], v[64:65]
	v_add_f32_e32 v59, v59, v63
	v_add_f32_e32 v59, v59, v152
	v_and_b32_e32 v136, 0xffff0000, v69
	v_add_f32_e32 v59, v59, v153
	v_pk_mul_f32 v[138:139], v[136:137], v[136:137]
	v_and_b32_e32 v145, 0xffff0000, v66
	v_lshlrev_b32_e32 v144, 16, v66
	v_fmac_f32_e32 v59, v1, v1
	v_pk_mul_f32 v[146:147], v[144:145], v[144:145]
	v_add_f32_e32 v59, v59, v139
	v_and_b32_e32 v151, 0xffff0000, v67
	v_lshlrev_b32_e32 v150, 16, v67
	v_add_f32_e32 v59, v59, v146
	v_pk_mul_f32 v[66:67], v[150:151], v[150:151]
	v_add_f32_e32 v59, v59, v147
	v_and_b32_e32 v155, 0xffff0000, v68
	v_lshlrev_b32_e32 v154, 16, v68
	v_add_f32_e32 v59, v59, v66
	v_lshlrev_b32_e32 v3, 16, v69
	v_pk_mul_f32 v[68:69], v[154:155], v[154:155]
	v_add_f32_e32 v59, v59, v67
	v_add_f32_e32 v59, v59, v68
	v_add_f32_e32 v59, v59, v69
	v_fmac_f32_e32 v59, v3, v3
	v_pk_mul_f32 v[56:57], v[54:55], v[54:55]
	v_add_f32_e32 v59, v59, v138
	v_add_f32_e32 v56, v59, v56
	v_pk_mul_f32 v[78:79], v[52:53], v[52:53]
	v_add_f32_e32 v56, v56, v57
	v_add_f32_e32 v56, v56, v78
	v_pk_mul_f32 v[90:91], v[50:51], v[50:51]
	v_add_f32_e32 v56, v56, v79
	v_add_f32_e32 v56, v56, v90
	v_pk_mul_f32 v[92:93], v[48:49], v[48:49]
	v_add_f32_e32 v56, v56, v91
	v_add_f32_e32 v56, v56, v92
	v_pk_mul_f32 v[94:95], v[46:47], v[46:47]
	v_add_f32_e32 v56, v56, v93
	v_add_f32_e32 v56, v56, v94
	v_pk_mul_f32 v[96:97], v[44:45], v[44:45]
	v_add_f32_e32 v56, v56, v95
	v_add_f32_e32 v56, v56, v96
	v_pk_mul_f32 v[98:99], v[42:43], v[42:43]
	v_add_f32_e32 v56, v56, v97
	v_add_f32_e32 v56, v56, v98
	v_pk_mul_f32 v[100:101], v[40:41], v[40:41]
	v_add_f32_e32 v56, v56, v99
	v_add_f32_e32 v56, v56, v100
	v_pk_mul_f32 v[102:103], v[38:39], v[38:39]
	v_add_f32_e32 v56, v56, v101
	v_add_f32_e32 v56, v56, v102
	v_pk_mul_f32 v[104:105], v[36:37], v[36:37]
	v_add_f32_e32 v56, v56, v103
	v_add_f32_e32 v56, v56, v104
	v_pk_mul_f32 v[106:107], v[34:35], v[34:35]
	v_add_f32_e32 v56, v56, v105
	v_add_f32_e32 v56, v56, v106
	v_pk_mul_f32 v[108:109], v[32:33], v[32:33]
	v_add_f32_e32 v56, v56, v107
	v_add_f32_e32 v56, v56, v108
	v_pk_mul_f32 v[110:111], v[30:31], v[30:31]
	v_add_f32_e32 v56, v56, v109
	v_add_f32_e32 v56, v56, v110
	v_pk_mul_f32 v[112:113], v[28:29], v[28:29]
	v_add_f32_e32 v56, v56, v111
	v_add_f32_e32 v56, v56, v112
	v_pk_mul_f32 v[114:115], v[26:27], v[26:27]
	v_add_f32_e32 v56, v56, v113
	v_add_f32_e32 v56, v56, v114
	v_pk_mul_f32 v[116:117], v[24:25], v[24:25]
	v_add_f32_e32 v56, v56, v115
	v_add_f32_e32 v56, v56, v116
	v_pk_mul_f32 v[118:119], v[22:23], v[22:23]
	v_add_f32_e32 v56, v56, v117
	v_add_f32_e32 v56, v56, v118
	v_pk_mul_f32 v[120:121], v[20:21], v[20:21]
	v_add_f32_e32 v56, v56, v119
	v_add_f32_e32 v56, v56, v120
	v_pk_mul_f32 v[122:123], v[18:19], v[18:19]
	v_add_f32_e32 v56, v56, v121
	v_add_f32_e32 v56, v56, v122
	v_pk_mul_f32 v[124:125], v[16:17], v[16:17]
	v_add_f32_e32 v56, v56, v123
	v_add_f32_e32 v56, v56, v124
	v_pk_mul_f32 v[126:127], v[8:9], v[8:9]
	v_add_f32_e32 v56, v56, v125
	v_add_f32_e32 v56, v56, v126
	v_pk_mul_f32 v[130:131], v[10:11], v[10:11]
	v_add_f32_e32 v56, v56, v127
	v_add_f32_e32 v56, v56, v130
	v_pk_mul_f32 v[132:133], v[12:13], v[12:13]
	v_add_f32_e32 v56, v56, v131
	v_add_f32_e32 v56, v56, v132
	v_pk_mul_f32 v[134:135], v[14:15], v[14:15]
	v_add_f32_e32 v56, v56, v133
	v_add_f32_e32 v56, v56, v134
	v_add_f32_e32 v56, v56, v135
	v_fmamk_f32 v56, v56, 0x3c800000, v220
	v_mul_f32_e32 v57, 0x4b800000, v56
	v_cmp_gt_f32_e32 vcc, s2, v56
	s_waitcnt vmcnt(7)
	v_mov_b32_e32 v62, v85
	s_waitcnt vmcnt(5)
	v_mov_b32_e32 v63, v207
	v_cndmask_b32_e32 v56, v56, v57, vcc
	v_rsq_f32_e32 v56, v56
	s_nop 0
	v_mul_f32_e32 v57, 0x45800000, v56
	v_cndmask_b32_e32 v56, v56, v57, vcc
	v_pk_mul_f32 v[66:67], v[56:57], v[140:141] op_sel_hi:[0,1]
	v_pk_mul_f32 v[64:65], v[56:57], v[64:65] op_sel_hi:[0,1]
	s_waitcnt vmcnt(4)
	v_pk_mul_f32 v[78:79], v[208:209], v[66:67]
	v_pk_mul_f32 v[66:67], v[56:57], v[148:149] op_sel_hi:[0,1]
	v_pk_mul_f32 v[74:75], v[204:205], v[64:65]
	v_mul_f32_e32 v1, v56, v1
	v_pk_mul_f32 v[64:65], v[56:57], v[136:137] op_sel_hi:[0,1]
	v_pk_mul_f32 v[76:77], v[210:211], v[66:67]
	v_mul_f32_e32 v72, v206, v1
	v_pk_mul_f32 v[68:69], v[64:65], v[62:63]
	v_pk_mul_f32 v[62:63], v[56:57], v[144:145] op_sel_hi:[0,1]
	v_pk_mul_f32 v[64:65], v[56:57], v[150:151] op_sel_hi:[0,1]
	v_pk_mul_f32 v[66:67], v[56:57], v[154:155] op_sel_hi:[0,1]
	v_mul_f32_e32 v1, v56, v3
	v_pk_mul_f32 v[62:63], v[86:87], v[62:63]
	v_pk_mul_f32 v[64:65], v[88:89], v[64:65]
	v_pk_mul_f32 v[66:67], v[82:83], v[66:67]
	v_mul_f32_e32 v70, v1, v84
	v_cmp_lt_i32_e32 vcc, 7, v58
	s_and_saveexec_b64 s[50:51], vcc
	s_cbranch_execz .LBB0_350
	v_lshlrev_b64 v[58:59], 6, v[60:61]
	v_lshl_add_u64 v[90:91], s[46:47], 0, v[58:59]
	v_mov_b32_e32 v71, v68
	v_mov_b32_e32 v73, v69
	s_waitcnt vmcnt(2)
	v_pk_mul_f32 v[94:95], v[62:63], v[240:241]
	s_waitcnt vmcnt(0)
	v_pk_fma_f32 v[94:95], v[78:79], v[248:249], v[94:95] neg_lo:[0,0,1] neg_hi:[0,0,1]
	v_pk_mul_f32 v[78:79], v[78:79], v[240:241]
	s_nop 0
	v_pk_fma_f32 v[62:63], v[62:63], v[248:249], v[78:79]
	v_pk_mul_f32 v[78:79], v[64:65], v[242:243]
	s_nop 0
	v_pk_fma_f32 v[82:83], v[76:77], v[250:251], v[78:79] neg_lo:[0,0,1] neg_hi:[0,0,1]
	v_pk_mul_f32 v[76:77], v[76:77], v[242:243]
	v_mov_b32_e32 v78, v94
	v_pk_fma_f32 v[64:65], v[64:65], v[250:251], v[76:77]
	v_pk_mul_f32 v[76:77], v[66:67], v[212:213]
	v_pk_mul_f32 v[58:59], v[74:75], v[212:213]
	v_pk_fma_f32 v[84:85], v[74:75], v[244:245], v[76:77] neg_lo:[0,0,1] neg_hi:[0,0,1]
	v_pk_fma_f32 v[66:67], v[66:67], v[244:245], v[58:59]
	v_pk_mul_f32 v[58:59], v[70:71], v[214:215]
	v_mul_f32_e32 v70, v70, v246
	v_pk_fma_f32 v[58:59], v[72:73], v[246:247], v[58:59] neg_lo:[0,0,1] neg_hi:[0,0,1]
	v_mul_f32_e32 v72, v72, v214
	v_mov_b32_e32 v60, v247
	v_mov_b32_e32 v61, v215
	v_pk_mul_f32 v[60:61], v[68:69], v[60:61]
	v_mov_b32_e32 v79, v95
	v_mov_b32_e32 v71, v60
	v_mov_b32_e32 v73, v61
	v_pk_add_f32 v[70:71], v[70:71], v[72:73]
	v_mov_b32_e32 v76, v82
	v_mov_b32_e32 v77, v83
	v_mov_b32_e32 v74, v84
	v_mov_b32_e32 v75, v85
	v_mov_b32_e32 v72, v58
	v_mov_b32_e32 v69, v59
	v_mov_b32_e32 v68, v71
	s_branch .LBB0_350
